# baseline (speedup 1.0000x reference)
;     __device__ __forceinline__ bf16_t* Ksf() const { return (bf16_t*)(ws + OFF_Ksf); }
;     __device__ __forceinline__ bf16_t* VsfT() const { return (bf16_t*)(ws + OFF_VsfT); }
;     __device__ __forceinline__ bf16_t* Ksb() const { return (bf16_t*)(ws + OFF_Ksb); }
;     __device__ __forceinline__ bf16_t* VsbT() const { return (bf16_t*)(ws + OFF_VsbT); }
; DEV int tid_opaque() { int t = threadIdx.x; asm volatile("" : "+v"(t)); return t; }
; DEV void st_bf4(bf16_t* p, float a, float b, float c, float d) { uint2 w; w.x = pk_bf16(a, b); w.y = pk_bf16(c, d); *(uint2*)p = w; }
; DEV void cache_convert(const Params& p, int l, int vb, int vnb, float* sm) {
;     const int gt = vb * 256 + tid_opaque(), gn = vnb * 256;
;     for (int i = gt; i < 8 * PAST * 96; i += gn) {
;         const int b = i / (PAST * 96), rem = i % (PAST * 96);
;         const float4 v = *(const float4*)(p.cache_fox_k + ((size_t)(l * 8 + b) * PAST * 384) + (size_t)rem * 4);
;         st_bf4(p.Ksf() + (size_t)b * KSP * 384 + (size_t)rem * 4, v.x, v.y, v.z, v.w);
;     }
;     for (int i = gt; i < 8 * PAST * 64; i += gn) {
;         const int b = i / (PAST * 64), rem = i % (PAST * 64);
;         const float4 v = *(const float4*)(p.cache_sb_k + ((size_t)(l * 8 + b) * PAST * 256) + (size_t)rem * 4);
;         st_bf4(p.Ksb() + (size_t)b * KSP * 256 + (size_t)rem * 4, v.x, v.y, v.z, v.w);
;     }
;     for (int i = gt; i < 8 * 48 * 384; i += gn) { const int b = i / (48 * 384), rem = i % (48 * 384); p.Ksf()[(size_t)b * KSP * 384 + (size_t)2064 * 384 + rem] = 0; }
;     for (int i = gt; i < 8 * 48 * 256; i += gn) { const int b = i / (48 * 256), rem = i % (48 * 256); p.Ksb()[(size_t)b * KSP * 256 + (size_t)2064 * 256 + rem] = 0; }
;     for (int i = gt; i < 8 * 384 * 48; i += gn) { const int row = i / 48, c = i % 48; p.VsfT()[(size_t)row * KSP + 2064 + c] = 0; }
;     for (int i = gt; i < 8 * 256 * 48; i += gn) { const int row = i / 48, c = i % 48; p.VsbT()[(size_t)row * KSP + 2064 + c] = 0; }
;     for (int job = vb; job < 8 * 192 + 8 * 128; job += vnb) {
; __global__ void __launch_bounds__(256, 2) fwd_kernel(Params p) {
;     ...
;         if (ph == 0 || (ph == 8 && bid >= 64)) cache_convert(pq, ph == 0 ? 0 : 1, ph == 0 ? bid : bid - 64, ph == 0 ? nb : nb - 64, (float*)smem);
.LBB0_2706:
	v_readlane_b32 s0, v254, 6
	v_readlane_b32 s1, v254, 7
	s_andn2_b64 vcc, exec, s[0:1]
	s_mov_b64 s[0:1], s[94:95]
	s_cbranch_vccnz .LBB0_2708
	s_cmp_eq_u32 s82, 4
	s_cselect_b64 s[0:1], -1, 0
	s_cmp_gt_i32 s78, 15
	s_cselect_b64 s[2:3], -1, 0
	s_and_b64 s[0:1], s[0:1], s[2:3]
	s_cmp_eq_u32 s82, 8
	s_cselect_b64 s[2:3], -1, 0
	s_cmp_gt_i32 s78, 63
	s_cselect_b64 s[4:5], -1, 0
	s_and_b64 s[2:3], s[2:3], s[4:5]
	s_or_b64 s[0:1], s[0:1], s[2:3]
.LBB0_2708:
	s_andn2_b64 vcc, exec, s[0:1]
	v_readlane_b32 s4, v254, 4
	v_readlane_b32 s5, v254, 5
	s_cbranch_vccnz .LBB0_2750
	s_cmp_eq_u32 s82, 8
	s_cselect_b32 s3, 64, 16
	s_sub_i32 s2, s78, s3
	s_and_b64 s[0:1], s[94:95], exec
	s_cselect_b32 s6, s78, s2
	s_sub_i32 s2, s4, s3
	v_mov_b32_e32 v0, v186
	s_and_b64 s[0:1], s[94:95], exec
	s_cselect_b32 s7, s4, s2
	s_and_b64 s[0:1], s[94:95], exec
	s_cbranch_scc0 .Lcc_skip
	s_addk_i32 s7, 0xff40
	s_cmp_ge_i32 s6, s7
	s_cselect_b32 s6, 0x10000, s6
.Lcc_skip:
	v_lshl_add_u32 v0, s6, 8, v0
	s_cmp_eq_u32 s82, 8
	s_cbranch_scc0 .Lcc_e
	v_mov_b32_e32 v0, 0x1000000
.Lcc_e:
	s_mov_b32 s0, 0x180000
	s_lshl_b32 s8, s7, 8
	v_cmp_gt_i32_e32 vcc, s0, v0
	s_and_saveexec_b64 s[0:1], vcc
	s_movk_i32 s12, 0x300
	s_mov_b32 s13, 0x2aaaaaab
	s_cbranch_execz .LBB0_2712
	s_and_b64 s[2:3], s[94:95], exec
	v_readlane_b32 s2, v254, 1
	s_cselect_b32 s9, 0, 8
	v_readlane_b32 s3, v254, 2
	s_add_u32 s2, s2, 0x1362c000
	s_addc_u32 s3, s3, 0
	s_mov_b64 s[4:5], 0
	v_mov_b32_e32 v1, v0

;     __device__ __forceinline__ bf16_t* VsfT() const { return (bf16_t*)(ws + OFF_VsfT); }
;     __device__ __forceinline__ bf16_t* VsbT() const { return (bf16_t*)(ws + OFF_VsbT); }
; DEV void cache_convert(const Params& p, int l, int vb, int vnb, float* sm) {
;     ...
;     for (int job = vb; job < 8 * 192 + 8 * 128; job += vnb) {
;         const bool fox = job < 8 * 192;
;         const int jj = fox ? job : job - 8 * 192, per = fox ? 192 : 128, W = fox ? 384 : 256;
;         const int b = jj / per, r = jj % per, tn = r / 32, tk = r % 32;
;         const float* src = (fox ? p.cache_fox_v : p.cache_sb_v) + (size_t)(l * 8 + b) * PAST * W + (size_t)tk * 64 * W;
;         bf16_t* dst = (fox ? p.VsfT() : p.VsbT()) + ((size_t)b * W + tn * 64) * KSP + tk * 64;
;         transpose_tile(src, W, tn * 64, tn * 64 + 32, dst, KSP, sm);
;     }
.LBB0_2747:
	s_or_b64 exec, exec, s[0:1]
	s_cmp_eq_u32 s82, 4
	s_cbranch_scc1 .LBB0_2750
	s_cmpk_gt_i32 s6, 0x9ff
	s_cbranch_scc1 .LBB0_2750
	s_and_b64 s[0:1], s[94:95], exec
	s_cselect_b32 s0, 0, 8
	s_movk_i32 s14, 0x180
	s_movk_i32 s15, 0x1080
	s_movk_i32 s16, 0x104
